# prompt chunk also touches the Q lines of the chunk 8 tasks ahead (cache warm-up), youngest VMEM op so later waits leave it in flight
# baseline (speedup 1.0000x reference)
.LBB0_728:
	s_or_b64 exec, exec, s[12:13]
	v_readfirstlane_b32 s14, v0
	s_cmp_ge_i32 s14, s22
	s_mov_b64 s[12:13], -1
	s_cbranch_scc1 .LBB0_723
	s_cmp_ge_i32 s14, s21
	v_lshlrev_b32_e32 v92, 1, v138
	v_mbcnt_hi_u32_b32 v102, -1, v220
	s_cbranch_scc0 .LBB0_731
	s_sub_i32 s12, s14, s21
	s_and_b32 s15, s12, 3
	s_lshl_b32 s13, s15, 5
	v_or_b32_e32 v0, s13, v154
	s_lshr_b32 s12, s12, 2
	v_ashrrev_i32_e32 v1, 31, v0
	v_readlane_b32 s24, v254, 54
	v_lshlrev_b64 v[84:85], 12, v[0:1]
	v_readlane_b32 s25, v254, 55
	s_add_i32 s12, s12, s23
	v_mov_b32_e32 v93, v131
	v_lshl_add_u64 v[0:1], s[24:25], 0, v[84:85]
	s_lshl_b32 s24, s12, 7
	s_mov_b32 s25, s92
	v_lshl_add_u64 v[0:1], v[0:1], 0, s[24:25]
	v_lshl_add_u64 v[90:91], v[0:1], 0, v[92:93]
	global_load_dwordx4 v[68:71], v[90:91], off
	global_load_dwordx4 v[64:67], v[90:91], off offset:32
	s_add_i32 s93, s15, 1
	v_lshl_or_b32 v4, s93, 5, v136
	v_mad_u32_u24 v94, v4, s16, v129
	ds_read_b128 v[16:19], v94
	ds_read_b128 v[76:79], v94 offset:32
	s_add_i32 s94, s15, 2
	v_lshl_or_b32 v20, s94, 5, v136
	v_mad_u32_u24 v95, v20, s16, v129
	v_or_b32_e32 v2, s13, v136
	s_add_i32 s95, s15, 3
	v_mad_u32_u24 v93, v2, s16, v129
	v_lshl_or_b32 v20, s95, 5, v136
	ds_read_b128 v[0:3], v93
	ds_read_b128 v[72:75], v93 offset:32
	v_mad_u32_u24 v96, v20, s16, v129
	s_mov_b32 s13, s92
	v_readlane_b32 s56, v254, 22
	s_or_b32 s24, s15, 4
	s_lshl_b64 vcc, s[12:13], 2
	v_readlane_b32 s58, v254, 24
	v_readlane_b32 s59, v254, 25
	s_add_u32 vcc_lo, s58, vcc_lo
	s_addc_u32 vcc_hi, s59, vcc_hi
	s_cmp_eq_u32 s15, 3
	v_readlane_b32 s57, v254, 23
	v_readlane_b32 s56, v255, 4
	v_readlane_b32 s57, v255, 5
	v_readlane_b32 s60, v254, 26
	v_readlane_b32 s61, v254, 27
	v_readlane_b32 s62, v254, 28
	v_readlane_b32 s63, v254, 29
	v_readlane_b32 s64, v254, 30
	v_readlane_b32 s65, v254, 31
	v_readlane_b32 s66, v254, 32
	v_readlane_b32 s67, v254, 33
	v_readlane_b32 s68, v254, 34
	v_readlane_b32 s69, v254, 35
	v_readlane_b32 s70, v254, 36
	v_readlane_b32 s71, v254, 37
	s_waitcnt vmcnt(1) lgkmcnt(3)
	v_mfma_f32_32x32x16_bf16 v[48:63], v[16:19], v[68:71], 0
	ds_read_b128 v[16:19], v95
	ds_read_b128 v[80:83], v95 offset:32
	s_waitcnt lgkmcnt(1)
	v_mfma_f32_32x32x16_bf16 v[32:47], v[16:19], v[68:71], 0
	ds_read_b128 v[16:19], v96
	ds_read_b128 v[86:89], v96 offset:32
	s_waitcnt vmcnt(0)
	v_mfma_f32_32x32x16_bf16 v[48:63], v[76:79], v[64:67], v[48:63]
	global_load_dwordx4 v[76:79], v[90:91], off offset:64
	v_mfma_f32_32x32x16_bf16 v[0:15], v[0:3], v[68:71], 0
	v_mfma_f32_32x32x16_bf16 v[0:15], v[72:75], v[64:67], v[0:15]
	global_load_dwordx4 v[72:75], v[90:91], off offset:96
	s_waitcnt lgkmcnt(1)
	v_mfma_f32_32x32x16_bf16 v[16:31], v[16:19], v[68:71], 0
	v_mfma_f32_32x32x16_bf16 v[32:47], v[80:83], v[64:67], v[32:47]
	s_waitcnt lgkmcnt(0)
	v_mfma_f32_32x32x16_bf16 v[16:31], v[86:89], v[64:67], v[16:31]
	ds_read_b128 v[86:89], v93 offset:64
	ds_read_b128 v[80:83], v93 offset:96
	s_waitcnt vmcnt(1) lgkmcnt(1)
	v_mfma_f32_32x32x16_bf16 v[0:15], v[86:89], v[76:79], v[0:15]
	ds_read_b128 v[86:89], v94 offset:64
	ds_read_b128 v[98:101], v94 offset:96
	s_waitcnt lgkmcnt(1)
	v_mfma_f32_32x32x16_bf16 v[48:63], v[86:89], v[76:79], v[48:63]
	ds_read_b128 v[86:89], v95 offset:64
	ds_read_b128 v[104:107], v95 offset:96
	s_waitcnt lgkmcnt(1)
	v_mfma_f32_32x32x16_bf16 v[32:47], v[86:89], v[76:79], v[32:47]
	ds_read_b128 v[86:89], v96 offset:64
	ds_read_b128 v[112:115], v96 offset:96
	global_load_dword v96, v131, vcc
	global_load_dwordx4 v[184:187], v[90:91], off offset:256
	s_cselect_b64 vcc, -1, 0
	s_or_b64 vcc, s[8:9], vcc
	s_xor_b32 s13, s15, 2
	s_cmp_lt_u32 s13, 2
	s_waitcnt lgkmcnt(1)
	v_mfma_f32_32x32x16_bf16 v[16:31], v[86:89], v[76:79], v[16:31]
	s_waitcnt vmcnt(2)
	v_mfma_f32_32x32x16_bf16 v[48:63], v[98:101], v[72:75], v[48:63]
	v_mfma_f32_32x32x16_bf16 v[32:47], v[104:107], v[72:75], v[32:47]
	s_nop 10
	v_cndmask_b32_e32 v48, v179, v48, vcc
	v_cndmask_b32_e32 v49, v179, v49, vcc
	v_cndmask_b32_e32 v50, v179, v50, vcc
	v_cndmask_b32_e32 v51, v179, v51, vcc
	v_cndmask_b32_e32 v52, v179, v52, vcc
	v_cndmask_b32_e32 v53, v179, v53, vcc
	v_cndmask_b32_e32 v54, v179, v54, vcc
	s_waitcnt lgkmcnt(0)
	v_mfma_f32_32x32x16_bf16 v[16:31], v[112:115], v[72:75], v[16:31]
	v_cndmask_b32_e32 v55, v179, v55, vcc
	v_cndmask_b32_e32 v56, v179, v56, vcc
	v_cndmask_b32_e32 v57, v179, v57, vcc
	v_cndmask_b32_e32 v58, v179, v58, vcc
	v_cndmask_b32_e32 v59, v179, v59, vcc
	v_cndmask_b32_e32 v60, v179, v60, vcc
	v_cndmask_b32_e32 v61, v179, v61, vcc
	v_cndmask_b32_e32 v62, v179, v62, vcc
	v_cndmask_b32_e32 v116, v179, v63, vcc
	s_cselect_b64 vcc, -1, 0
	s_or_b64 vcc, s[8:9], vcc
	s_or_b32 s13, s15, s20
	s_cmp_eq_u32 s13, 0
	v_cndmask_b32_e32 v117, v179, v32, vcc
	v_cndmask_b32_e32 v118, v179, v33, vcc
	v_cndmask_b32_e32 v119, v179, v34, vcc
	v_cndmask_b32_e32 v120, v179, v35, vcc
	v_cndmask_b32_e32 v121, v179, v36, vcc
	v_cndmask_b32_e32 v122, v179, v37, vcc
	v_cndmask_b32_e32 v123, v179, v38, vcc
	v_cndmask_b32_e32 v130, v179, v39, vcc
	v_cndmask_b32_e32 v63, v179, v40, vcc
	v_cndmask_b32_e32 v111, v179, v41, vcc
	v_cndmask_b32_e32 v110, v179, v42, vcc
	v_cndmask_b32_e32 v109, v179, v43, vcc
	v_cndmask_b32_e32 v108, v179, v44, vcc
	v_cndmask_b32_e32 v107, v179, v45, vcc
	v_cndmask_b32_e32 v106, v179, v46, vcc
	v_cndmask_b32_e32 v105, v179, v47, vcc
	s_cselect_b64 vcc, -1, 0
	v_cndmask_b32_e32 v103, v17, v179, vcc
	v_and_b32_e32 v17, 64, v102
	v_cndmask_b32_e32 v104, v16, v179, vcc
	v_xor_b32_e32 v16, 32, v102
	v_add_u32_e32 v17, 64, v17
	v_cndmask_b32_e32 v101, v18, v179, vcc
	v_cndmask_b32_e32 v100, v19, v179, vcc
	v_cndmask_b32_e32 v99, v20, v179, vcc
	v_cndmask_b32_e32 v98, v21, v179, vcc
	v_cndmask_b32_e32 v97, v22, v179, vcc
	v_cndmask_b32_e32 v95, v23, v179, vcc
	v_cndmask_b32_e32 v94, v24, v179, vcc
	v_cndmask_b32_e32 v93, v25, v179, vcc
	v_cndmask_b32_e32 v91, v26, v179, vcc
	v_cndmask_b32_e32 v90, v27, v179, vcc
	v_cndmask_b32_e32 v86, v28, v179, vcc
	v_cndmask_b32_e32 v87, v29, v179, vcc
	v_cndmask_b32_e32 v88, v30, v179, vcc
	v_cndmask_b32_e32 v89, v31, v179, vcc
	v_cmp_lt_i32_e32 vcc, v16, v17
	v_mfma_f32_32x32x16_bf16 v[0:15], v[80:83], v[72:75], v[0:15]
	s_mov_b32 s13, 0x3fb8aa3b
	v_cndmask_b32_e32 v44, v102, v16, vcc
	v_lshl_or_b32 v16, s24, 5, v136
	v_mad_u32_u24 v40, v16, s16, v129
	ds_read_b128 v[16:19], v40
	ds_read_b128 v[32:35], v40 offset:32
	ds_read_b128 v[36:39], v40 offset:64
	ds_read_b128 v[40:43], v40 offset:96
	v_lshlrev_b32_e32 v112, 2, v44
	s_waitcnt lgkmcnt(3)
	v_mfma_f32_32x32x16_bf16 v[16:31], v[16:19], v[68:71], 0
	s_nop 0
	v_cndmask_b32_e64 v0, v179, v0, s[26:27]
	v_cndmask_b32_e64 v1, v179, v1, s[28:29]
	v_max3_f32 v45, v0, s17, v1
	v_cndmask_b32_e64 v2, v179, v2, s[30:31]
	v_cndmask_b32_e64 v3, v179, v3, s[34:35]
	v_cndmask_b32_e64 v4, v179, v4, s[36:37]
	v_cndmask_b32_e64 v5, v179, v5, s[38:39]
	s_waitcnt lgkmcnt(2)
	v_mfma_f32_32x32x16_bf16 v[16:31], v[32:35], v[64:67], v[16:31]
	v_max3_f32 v32, v45, v2, v3
	v_max3_f32 v32, v32, v4, v5
	v_cndmask_b32_e64 v6, v179, v6, s[96:97]
	v_cndmask_b32_e64 v7, v179, v7, s[2:3]
	v_max3_f32 v32, v32, v6, v7
	v_cndmask_b32_e64 v8, v179, v8, s[72:73]
	v_cndmask_b32_e64 v9, v179, v9, s[74:75]
	s_waitcnt lgkmcnt(1)
	v_mfma_f32_32x32x16_bf16 v[16:31], v[36:39], v[76:79], v[16:31]
	v_max3_f32 v32, v32, v8, v9
	v_cndmask_b32_e64 v34, v179, v10, s[76:77]
	v_cndmask_b32_e64 v11, v179, v11, s[78:79]
	v_max3_f32 v10, v32, v34, v11
	v_cndmask_b32_e64 v12, v179, v12, s[80:81]
	v_cndmask_b32_e64 v13, v179, v13, s[82:83]
	v_max3_f32 v10, v10, v12, v13
	s_waitcnt lgkmcnt(0)
	v_mfma_f32_32x32x16_bf16 v[16:31], v[40:43], v[72:75], v[16:31]
	v_cndmask_b32_e64 v14, v179, v14, s[84:85]
	v_cndmask_b32_e64 v15, v179, v15, s[86:87]
	v_max3_f32 v10, v10, v14, v15
	v_max3_f32 v10, v10, v48, v49
	v_max3_f32 v10, v10, v50, v51
	v_max3_f32 v10, v10, v52, v53
	v_max3_f32 v10, v10, v54, v55
	s_nop 4
	v_cndmask_b32_e64 v16, v16, v179, s[56:57]
	v_readlane_b32 s56, v255, 34
	v_readlane_b32 s57, v255, 35
	v_max3_f32 v10, v10, v56, v57
	v_max3_f32 v10, v10, v58, v59
	v_cndmask_b32_e64 v17, v179, v17, s[56:57]
	v_readlane_b32 s56, v255, 8
	v_readlane_b32 s57, v255, 9
	v_max3_f32 v10, v10, v60, v61
	v_max3_f32 v10, v10, v62, v116
	v_cndmask_b32_e64 v18, v18, v179, s[56:57]
	v_readlane_b32 s56, v255, 10
	v_readlane_b32 s57, v255, 11
	v_max3_f32 v10, v10, v117, v118
	v_max3_f32 v10, v10, v119, v120
	v_cndmask_b32_e64 v19, v19, v179, s[56:57]
	v_readlane_b32 s56, v255, 12
	v_readlane_b32 s57, v255, 13
	v_max3_f32 v10, v10, v121, v122
	v_max3_f32 v10, v10, v123, v130
	v_cndmask_b32_e64 v20, v20, v179, s[56:57]
	v_readlane_b32 s56, v255, 14
	v_readlane_b32 s57, v255, 15
	v_max3_f32 v10, v10, v63, v111
	v_max3_f32 v10, v10, v110, v109
	v_cndmask_b32_e64 v21, v21, v179, s[56:57]
	v_readlane_b32 s56, v255, 16
	v_readlane_b32 s57, v255, 17
	v_max3_f32 v10, v10, v108, v107
	v_max3_f32 v10, v10, v106, v105
	v_cndmask_b32_e64 v22, v22, v179, s[56:57]
	v_readlane_b32 s56, v255, 18
	v_readlane_b32 s57, v255, 19
	v_max3_f32 v10, v10, v104, v103
	v_max3_f32 v10, v10, v101, v100
	v_cndmask_b32_e64 v23, v23, v179, s[56:57]
	v_readlane_b32 s56, v255, 20
	v_readlane_b32 s57, v255, 21
	v_max3_f32 v10, v10, v99, v98
	v_max3_f32 v10, v10, v97, v95
	v_cndmask_b32_e64 v24, v24, v179, s[56:57]
	v_readlane_b32 s56, v255, 22
	v_readlane_b32 s57, v255, 23
	v_max3_f32 v10, v10, v94, v93
	v_max3_f32 v10, v10, v91, v90
	v_cndmask_b32_e64 v25, v25, v179, s[56:57]
	v_readlane_b32 s56, v255, 24
	v_readlane_b32 s57, v255, 25
	v_max3_f32 v10, v10, v86, v87
	v_max3_f32 v10, v10, v88, v89
	v_cndmask_b32_e64 v26, v26, v179, s[56:57]
	v_readlane_b32 s56, v255, 26
	v_readlane_b32 s57, v255, 27
	v_max3_f32 v10, v10, v16, v17
	v_max3_f32 v10, v10, v18, v19
	v_cndmask_b32_e64 v27, v27, v179, s[56:57]
	v_readlane_b32 s56, v255, 28
	v_readlane_b32 s57, v255, 29
	v_max3_f32 v10, v10, v20, v21
	v_max3_f32 v10, v10, v22, v23
	v_cndmask_b32_e64 v28, v28, v179, s[56:57]
	v_readlane_b32 s56, v255, 30
	v_readlane_b32 s57, v255, 31
	v_max3_f32 v10, v10, v24, v25
	v_max3_f32 v10, v10, v26, v27
	v_cndmask_b32_e64 v29, v29, v179, s[56:57]
	v_readlane_b32 s56, v255, 32
	v_readlane_b32 s57, v255, 33
	v_max3_f32 v10, v10, v28, v29
	s_waitcnt vmcnt(1)
	v_mul_f32_e32 v33, 0x3fb8aa3b, v96
	v_cndmask_b32_e64 v30, v30, v179, s[56:57]
	v_readlane_b32 s56, v255, 2
	v_readlane_b32 s57, v255, 3
	v_lshl_add_u32 v115, s93, 6, v139
	v_lshl_or_b32 v114, s12, 6, v137
	v_cndmask_b32_e64 v31, v31, v179, s[56:57]
	v_max3_f32 v10, v10, v30, v31
	ds_bpermute_b32 v32, v112, v10
	s_waitcnt lgkmcnt(0)
	v_max_f32_e32 v32, v32, v32
	v_max_f32_e32 v10, v10, v32
	v_mul_f32_e32 v10, 0x3e38aa3b, v10
	v_max_f32_e32 v10, v10, v33
	v_fma_f32 v0, v0, s18, -v10
	v_exp_f32_e32 v0, v0
	v_fma_f32 v1, v1, s18, -v10
	v_exp_f32_e32 v1, v1
	v_fma_f32 v2, v2, s18, -v10
	v_exp_f32_e32 v2, v2
	v_fma_f32 v3, v3, s18, -v10
	v_exp_f32_e32 v3, v3
	v_fma_f32 v4, v4, s18, -v10
	v_add_f32_e32 v32, 0, v0
	v_exp_f32_e32 v4, v4
	v_fma_f32 v5, v5, s18, -v10
	v_add_f32_e32 v32, v1, v32
	v_exp_f32_e32 v5, v5
	v_fma_f32 v6, v6, s18, -v10
	v_add_f32_e32 v32, v2, v32
	v_exp_f32_e32 v6, v6
	v_fma_f32 v7, v7, s18, -v10
	v_add_f32_e32 v32, v3, v32
	v_exp_f32_e32 v7, v7
	v_add_f32_e32 v32, v4, v32
	v_add_f32_e32 v32, v5, v32
	v_add_f32_e32 v32, v6, v32
	v_fma_f32 v8, v8, s18, -v10
	v_add_f32_e32 v36, v7, v32
	v_exp_f32_e32 v32, v8
	v_fma_f32 v8, v9, s18, -v10
	v_exp_f32_e32 v33, v8
	v_fma_f32 v8, v34, s18, -v10
	v_exp_f32_e32 v34, v8
	v_fma_f32 v8, v11, s18, -v10
	v_exp_f32_e32 v35, v8
	v_fma_f32 v9, v12, s18, -v10
	v_add_f32_e32 v8, v32, v36
	v_exp_f32_e32 v36, v9
	v_fma_f32 v9, v13, s18, -v10
	v_add_f32_e32 v8, v33, v8
	v_exp_f32_e32 v37, v9
	v_fma_f32 v9, v14, s18, -v10
	v_add_f32_e32 v8, v34, v8
	v_exp_f32_e32 v38, v9
	v_fma_f32 v9, v15, s18, -v10
	v_add_f32_e32 v8, v35, v8
	v_exp_f32_e32 v40, v9
	v_fma_f32 v9, v48, s18, -v10
	v_add_f32_e32 v8, v36, v8
	v_exp_f32_e32 v39, v9
	v_fma_f32 v9, v49, s18, -v10
	v_add_f32_e32 v8, v37, v8
	v_exp_f32_e32 v41, v9
	v_fma_f32 v9, v50, s18, -v10
	v_add_f32_e32 v8, v38, v8
	v_exp_f32_e32 v42, v9
	v_fma_f32 v9, v51, s18, -v10
	v_add_f32_e32 v8, v40, v8
	v_exp_f32_e32 v43, v9
	v_fma_f32 v9, v52, s18, -v10
	v_add_f32_e32 v8, v39, v8
	v_exp_f32_e32 v44, v9
	v_fma_f32 v9, v53, s18, -v10
	v_add_f32_e32 v8, v41, v8
	v_exp_f32_e32 v45, v9
	v_fma_f32 v9, v54, s18, -v10
	v_add_f32_e32 v8, v42, v8
	v_exp_f32_e32 v46, v9
	v_fma_f32 v9, v55, s18, -v10
	v_add_f32_e32 v8, v43, v8
	v_exp_f32_e32 v48, v9
	v_fma_f32 v9, v56, s18, -v10
	v_add_f32_e32 v8, v44, v8
	v_exp_f32_e32 v47, v9
	v_fma_f32 v9, v57, s18, -v10
	v_add_f32_e32 v8, v45, v8
	v_exp_f32_e32 v49, v9
	v_fma_f32 v9, v58, s18, -v10
	v_add_f32_e32 v8, v46, v8
	v_exp_f32_e32 v50, v9
	v_fma_f32 v9, v59, s18, -v10
	v_add_f32_e32 v8, v48, v8
	v_exp_f32_e32 v51, v9
	v_fma_f32 v9, v60, s18, -v10
	v_add_f32_e32 v8, v47, v8
	v_exp_f32_e32 v52, v9
	v_fma_f32 v9, v61, s18, -v10
	v_add_f32_e32 v8, v49, v8
	v_exp_f32_e32 v53, v9
	v_fma_f32 v9, v62, s18, -v10
	v_add_f32_e32 v8, v50, v8
	v_exp_f32_e32 v54, v9
	v_fma_f32 v9, v116, s18, -v10
	v_add_f32_e32 v8, v51, v8
	v_exp_f32_e32 v56, v9
	v_fma_f32 v9, v117, s18, -v10
	v_add_f32_e32 v8, v52, v8
	v_exp_f32_e32 v55, v9
	v_fma_f32 v9, v118, s18, -v10
	v_add_f32_e32 v8, v53, v8
	v_exp_f32_e32 v57, v9
	v_fma_f32 v9, v119, s18, -v10
	v_add_f32_e32 v8, v54, v8
	v_exp_f32_e32 v58, v9
	v_fma_f32 v9, v120, s18, -v10
	v_add_f32_e32 v8, v56, v8
	v_exp_f32_e32 v59, v9
	v_fma_f32 v9, v121, s18, -v10
	v_add_f32_e32 v8, v55, v8
	v_exp_f32_e32 v60, v9
	v_fma_f32 v9, v122, s18, -v10
	v_add_f32_e32 v8, v57, v8
	v_exp_f32_e32 v61, v9
	v_fma_f32 v9, v123, s18, -v10
	v_add_f32_e32 v8, v58, v8
	v_exp_f32_e32 v62, v9
	v_fma_f32 v9, v130, s18, -v10
	v_add_f32_e32 v8, v59, v8
	v_exp_f32_e32 v64, v9
	v_fma_f32 v9, v63, s18, -v10
	v_add_f32_e32 v8, v60, v8
	v_exp_f32_e32 v63, v9
	v_fma_f32 v9, v111, s18, -v10
	v_add_f32_e32 v8, v61, v8
	v_exp_f32_e32 v65, v9
	v_fma_f32 v9, v110, s18, -v10
	v_add_f32_e32 v8, v62, v8
	v_exp_f32_e32 v66, v9
	v_fma_f32 v9, v109, s18, -v10
	v_add_f32_e32 v8, v64, v8
	v_exp_f32_e32 v67, v9
	v_fma_f32 v9, v108, s18, -v10
	v_add_f32_e32 v8, v63, v8
	v_exp_f32_e32 v68, v9
	v_fma_f32 v9, v107, s18, -v10
	v_add_f32_e32 v8, v65, v8
	v_exp_f32_e32 v69, v9
	v_fma_f32 v9, v106, s18, -v10
	v_add_f32_e32 v8, v66, v8
	v_exp_f32_e32 v70, v9
	v_fma_f32 v9, v105, s18, -v10
	v_add_f32_e32 v8, v67, v8
	v_exp_f32_e32 v72, v9
	v_fma_f32 v9, v104, s18, -v10
	v_add_f32_e32 v8, v68, v8
	v_exp_f32_e32 v71, v9
	v_fma_f32 v9, v103, s18, -v10
	v_add_f32_e32 v8, v69, v8
	v_exp_f32_e32 v73, v9
	v_fma_f32 v9, v101, s18, -v10
	v_add_f32_e32 v8, v70, v8
	v_exp_f32_e32 v74, v9
	v_fma_f32 v9, v100, s18, -v10
	v_add_f32_e32 v8, v72, v8
	v_exp_f32_e32 v75, v9
	v_fma_f32 v9, v99, s18, -v10
	v_add_f32_e32 v8, v71, v8
	v_exp_f32_e32 v76, v9
	v_fma_f32 v9, v98, s18, -v10
	v_add_f32_e32 v8, v73, v8
	v_exp_f32_e32 v77, v9
	v_fma_f32 v9, v97, s18, -v10
	v_add_f32_e32 v8, v74, v8
	v_exp_f32_e32 v78, v9
	v_fma_f32 v9, v95, s18, -v10
	v_add_f32_e32 v8, v75, v8
	v_exp_f32_e32 v80, v9
	v_fma_f32 v9, v94, s18, -v10
	v_add_f32_e32 v8, v76, v8
	v_exp_f32_e32 v79, v9
	v_fma_f32 v9, v93, s18, -v10
	v_add_f32_e32 v8, v77, v8
	v_exp_f32_e32 v81, v9
	v_fma_f32 v9, v91, s18, -v10
	v_add_f32_e32 v8, v78, v8
	v_exp_f32_e32 v82, v9
	v_fma_f32 v9, v90, s18, -v10
	v_add_f32_e32 v8, v80, v8
	v_exp_f32_e32 v83, v9
	v_fma_f32 v9, v86, s18, -v10
	v_add_f32_e32 v8, v79, v8
	v_exp_f32_e32 v86, v9
	v_fma_f32 v9, v87, s18, -v10
	v_add_f32_e32 v8, v81, v8
	v_exp_f32_e32 v87, v9
	v_fma_f32 v9, v88, s18, -v10
	v_add_f32_e32 v8, v82, v8
	v_exp_f32_e32 v88, v9
	v_fma_f32 v9, v89, s18, -v10
	v_add_f32_e32 v8, v83, v8
	v_exp_f32_e32 v90, v9
	v_fma_f32 v9, v16, s18, -v10
	v_add_f32_e32 v8, v86, v8
	v_exp_f32_e32 v89, v9
	v_fma_f32 v9, v17, s18, -v10
	v_add_f32_e32 v8, v87, v8
	v_exp_f32_e32 v91, v9
	v_fma_f32 v9, v18, s18, -v10
	v_add_f32_e32 v8, v88, v8
	v_exp_f32_e32 v93, v9
	v_fma_f32 v9, v19, s18, -v10
	v_add_f32_e32 v8, v90, v8
	v_exp_f32_e32 v94, v9
	v_fma_f32 v9, v20, s18, -v10
	v_add_f32_e32 v8, v89, v8
	v_exp_f32_e32 v95, v9
	v_fma_f32 v9, v21, s18, -v10
	v_add_f32_e32 v8, v91, v8
	v_exp_f32_e32 v97, v9
	v_fma_f32 v9, v22, s18, -v10
	v_add_f32_e32 v8, v93, v8
	v_exp_f32_e32 v98, v9
	v_fma_f32 v9, v23, s18, -v10
	v_add_f32_e32 v8, v94, v8
	v_exp_f32_e32 v100, v9
	v_fma_f32 v9, v24, s18, -v10
	v_add_f32_e32 v8, v95, v8
	v_exp_f32_e32 v99, v9
	v_fma_f32 v9, v25, s18, -v10
	v_add_f32_e32 v8, v97, v8
	v_exp_f32_e32 v101, v9
	v_fma_f32 v9, v26, s18, -v10
	v_add_f32_e32 v8, v98, v8
	v_exp_f32_e32 v103, v9
	v_fma_f32 v9, v27, s18, -v10
	v_add_f32_e32 v8, v100, v8
	v_exp_f32_e32 v104, v9
	v_fma_f32 v9, v28, s18, -v10
	v_add_f32_e32 v8, v99, v8
	v_exp_f32_e32 v105, v9
	v_fma_f32 v9, v29, s18, -v10
	v_add_f32_e32 v8, v101, v8
	v_exp_f32_e32 v106, v9
	v_fma_f32 v9, v30, s18, -v10
	v_add_f32_e32 v8, v103, v8
	v_exp_f32_e32 v107, v9
	v_fma_f32 v9, v31, s18, -v10
	v_add_f32_e32 v8, v104, v8
	v_exp_f32_e32 v108, v9
	v_add_f32_e32 v8, v105, v8
	v_add_f32_e32 v8, v106, v8
	v_add_f32_e32 v8, v107, v8
	v_add_f32_e32 v8, v108, v8
	ds_bpermute_b32 v9, v112, v8
	v_fma_f32 v10, v96, s13, -v10
	v_exp_f32_e32 v10, v10
	v_cvt_pk_bf16_f32 v0, v0, v1
	v_cvt_pk_bf16_f32 v1, v2, v3
	s_waitcnt lgkmcnt(0)
	v_add_f32_e32 v8, v8, v9
	v_add_f32_e32 v96, v10, v8
	v_div_scale_f32 v8, vcc, v96, v96, 1.0
	v_rcp_f32_e32 v9, v8
	v_cvt_pk_bf16_f32 v2, v4, v5
	v_cvt_pk_bf16_f32 v3, v6, v7
	v_cvt_pk_bf16_f32 v32, v32, v33
	v_fma_f32 v10, -v8, v9, 1.0
	v_fmac_f32_e32 v9, v10, v9
	v_div_scale_f32 v10, vcc, 1.0, v96, 1.0
	v_mul_f32_e32 v11, v10, v9
	v_fma_f32 v12, -v8, v11, v10
	v_fmac_f32_e32 v11, v12, v9
	v_fma_f32 v8, -v8, v11, v10
	v_lshl_add_u32 v12, s15, 6, v139
	v_div_fmas_f32 v109, v8, v9, v11
	v_add_u32_e32 v8, v12, v157
	v_add_u32_e32 v110, 0x9000, v8
	ds_read2_b64 v[8:11], v110 offset1:2
	v_add_u32_e32 v4, v12, v158
	v_add_u32_e32 v119, 0x9000, v4
	ds_read2_b64 v[110:113], v110 offset0:4 offset1:6
	s_waitcnt lgkmcnt(1)
	v_mfma_f32_32x32x16_bf16 v[16:31], v[8:11], v[0:3], 0
	ds_read2_b64 v[4:7], v119 offset1:2
	v_cvt_pk_bf16_f32 v33, v34, v35
	v_cvt_pk_bf16_f32 v34, v36, v37
	v_cvt_pk_bf16_f32 v35, v38, v40
	v_cvt_pk_bf16_f32 v36, v39, v41
	v_cvt_pk_bf16_f32 v37, v42, v43
	v_cvt_pk_bf16_f32 v38, v44, v45
	s_waitcnt lgkmcnt(1)
	v_mfma_f32_32x32x16_bf16 v[16:31], v[110:113], v[32:35], v[16:31]
	ds_read2_b64 v[110:113], v119 offset0:4 offset1:6
	v_cvt_pk_bf16_f32 v39, v46, v48
	v_lshl_add_u32 v116, s94, 6, v139
	v_lshl_add_u32 v117, s95, 6, v139
	v_lshl_add_u32 v118, s24, 6, v139
	v_readlane_b32 s12, v254, 52
	v_readlane_b32 s13, v254, 53
	s_waitcnt lgkmcnt(1)
	v_mfma_f32_32x32x16_bf16 v[0:15], v[4:7], v[0:3], 0
	v_lshlrev_b32_e32 v130, 1, v114
	s_waitcnt lgkmcnt(0)
	v_mfma_f32_32x32x16_bf16 v[0:15], v[110:113], v[32:35], v[0:15]
	v_add_u32_e32 v32, v115, v157
	v_add_u32_e32 v40, 0x9000, v32
	ds_read2_b64 v[32:35], v40 offset1:2
	s_waitcnt lgkmcnt(0)
	v_mfma_f32_32x32x16_bf16 v[16:31], v[32:35], v[36:39], v[16:31]
	v_add_u32_e32 v32, v115, v158
	v_add_u32_e32 v41, 0x9000, v32
	ds_read2_b64 v[32:35], v41 offset1:2
	s_waitcnt lgkmcnt(0)
	v_mfma_f32_32x32x16_bf16 v[0:15], v[32:35], v[36:39], v[0:15]
	ds_read2_b64 v[32:35], v40 offset0:4 offset1:6
	v_cvt_pk_bf16_f32 v36, v47, v49
	v_cvt_pk_bf16_f32 v37, v50, v51
	v_cvt_pk_bf16_f32 v38, v52, v53
	v_cvt_pk_bf16_f32 v39, v54, v56
	s_waitcnt lgkmcnt(0)
	s_nop 0
	v_mfma_f32_32x32x16_bf16 v[16:31], v[32:35], v[36:39], v[16:31]
	ds_read2_b64 v[32:35], v41 offset0:4 offset1:6
	s_waitcnt lgkmcnt(0)
	v_mfma_f32_32x32x16_bf16 v[0:15], v[32:35], v[36:39], v[0:15]
	v_add_u32_e32 v32, v116, v157
	v_add_u32_e32 v40, 0x9000, v32
	ds_read2_b64 v[32:35], v40 offset1:2
	v_cvt_pk_bf16_f32 v36, v55, v57
	v_cvt_pk_bf16_f32 v37, v58, v59
	v_cvt_pk_bf16_f32 v38, v60, v61
	v_cvt_pk_bf16_f32 v39, v62, v64
	s_waitcnt lgkmcnt(0)
	s_nop 0
	v_mfma_f32_32x32x16_bf16 v[16:31], v[32:35], v[36:39], v[16:31]
	v_add_u32_e32 v32, v116, v158
	v_add_u32_e32 v41, 0x9000, v32
	ds_read2_b64 v[32:35], v41 offset1:2
	s_waitcnt lgkmcnt(0)
	v_mfma_f32_32x32x16_bf16 v[0:15], v[32:35], v[36:39], v[0:15]
	ds_read2_b64 v[32:35], v40 offset0:4 offset1:6
	v_cvt_pk_bf16_f32 v36, v63, v65
	v_cvt_pk_bf16_f32 v37, v66, v67
	v_cvt_pk_bf16_f32 v38, v68, v69
	v_cvt_pk_bf16_f32 v39, v70, v72
	s_waitcnt lgkmcnt(0)
	s_nop 0
	v_mfma_f32_32x32x16_bf16 v[16:31], v[32:35], v[36:39], v[16:31]
	ds_read2_b64 v[32:35], v41 offset0:4 offset1:6
	s_waitcnt lgkmcnt(0)
	v_mfma_f32_32x32x16_bf16 v[0:15], v[32:35], v[36:39], v[0:15]
	v_add_u32_e32 v32, v117, v157
	v_add_u32_e32 v40, 0x9000, v32
	ds_read2_b64 v[32:35], v40 offset1:2
	v_cvt_pk_bf16_f32 v36, v71, v73
	v_cvt_pk_bf16_f32 v37, v74, v75
	v_cvt_pk_bf16_f32 v38, v76, v77
	v_cvt_pk_bf16_f32 v39, v78, v80
	s_waitcnt lgkmcnt(0)
	s_nop 0
	v_mfma_f32_32x32x16_bf16 v[16:31], v[32:35], v[36:39], v[16:31]
	v_add_u32_e32 v32, v117, v158
	v_add_u32_e32 v41, 0x9000, v32
	ds_read2_b64 v[32:35], v41 offset1:2
	s_waitcnt lgkmcnt(0)
	v_mfma_f32_32x32x16_bf16 v[0:15], v[32:35], v[36:39], v[0:15]
	ds_read2_b64 v[32:35], v40 offset0:4 offset1:6
	v_cvt_pk_bf16_f32 v36, v79, v81
	v_cvt_pk_bf16_f32 v37, v82, v83
	v_cvt_pk_bf16_f32 v38, v86, v87
	v_cvt_pk_bf16_f32 v39, v88, v90
	s_waitcnt lgkmcnt(0)
	s_nop 0
	v_mfma_f32_32x32x16_bf16 v[16:31], v[32:35], v[36:39], v[16:31]
	ds_read2_b64 v[32:35], v41 offset0:4 offset1:6
	s_waitcnt lgkmcnt(0)
	v_mfma_f32_32x32x16_bf16 v[0:15], v[32:35], v[36:39], v[0:15]
	v_add_u32_e32 v32, v118, v157
	v_add_u32_e32 v40, 0x9000, v32
	ds_read2_b64 v[32:35], v40 offset1:2
	v_cvt_pk_bf16_f32 v36, v89, v91
	v_cvt_pk_bf16_f32 v37, v93, v94
	v_cvt_pk_bf16_f32 v38, v95, v97
	v_cvt_pk_bf16_f32 v39, v98, v100
	s_waitcnt lgkmcnt(0)
	s_nop 0
	v_mfma_f32_32x32x16_bf16 v[16:31], v[32:35], v[36:39], v[16:31]
	v_add_u32_e32 v32, v118, v158
	v_add_u32_e32 v41, 0x9000, v32
	ds_read2_b64 v[32:35], v41 offset1:2
	s_waitcnt lgkmcnt(0)
	v_mfma_f32_32x32x16_bf16 v[0:15], v[32:35], v[36:39], v[0:15]
	ds_read2_b64 v[32:35], v40 offset0:4 offset1:6
	v_cvt_pk_bf16_f32 v36, v99, v101
	v_cvt_pk_bf16_f32 v37, v103, v104
	v_cvt_pk_bf16_f32 v38, v105, v106
	v_cvt_pk_bf16_f32 v39, v107, v108
	s_waitcnt lgkmcnt(0)
	s_nop 0
	v_mfma_f32_32x32x16_bf16 v[16:31], v[32:35], v[36:39], v[16:31]
	ds_read2_b64 v[32:35], v41 offset0:4 offset1:6
	s_waitcnt lgkmcnt(0)
	v_mfma_f32_32x32x16_bf16 v[0:15], v[32:35], v[36:39], v[0:15]
	v_div_fixup_f32 v32, v109, v96, 1.0
	v_lshl_add_u64 v[34:35], s[12:13], 0, v[84:85]
	s_nop 6
	v_pk_mul_f32 v[16:17], v[16:17], v[32:33] op_sel_hi:[1,0]
	v_pk_mul_f32 v[18:19], v[18:19], v[32:33] op_sel_hi:[1,0]
	v_pk_mul_f32 v[20:21], v[20:21], v[32:33] op_sel_hi:[1,0]
	v_pk_mul_f32 v[22:23], v[22:23], v[32:33] op_sel_hi:[1,0]
	v_pk_mul_f32 v[24:25], v[24:25], v[32:33] op_sel_hi:[1,0]
	v_pk_mul_f32 v[26:27], v[26:27], v[32:33] op_sel_hi:[1,0]
	v_pk_mul_f32 v[28:29], v[28:29], v[32:33] op_sel_hi:[1,0]
	v_pk_mul_f32 v[30:31], v[30:31], v[32:33] op_sel_hi:[1,0]
	v_and_b32_e32 v152, 32, v102
	v_lshrrev_b32_e32 v152, 2, v152
	v_mov_b32_e32 v153, 0
	v_lshl_add_u64 v[200:201], v[34:35], 0, v[130:131]
	v_pk_mul_f32 v[0:1], v[0:1], v[32:33] op_sel_hi:[1,0]
	v_pk_mul_f32 v[2:3], v[2:3], v[32:33] op_sel_hi:[1,0]
	v_pk_mul_f32 v[4:5], v[4:5], v[32:33] op_sel_hi:[1,0]
	v_pk_mul_f32 v[6:7], v[6:7], v[32:33] op_sel_hi:[1,0]
	v_pk_mul_f32 v[8:9], v[8:9], v[32:33] op_sel_hi:[1,0]
	v_pk_mul_f32 v[10:11], v[10:11], v[32:33] op_sel_hi:[1,0]
	v_pk_mul_f32 v[12:13], v[12:13], v[32:33] op_sel_hi:[1,0]
	v_pk_mul_f32 v[14:15], v[14:15], v[32:33] op_sel_hi:[1,0]
	v_cvt_pk_bf16_f32 v144, v16, v17
	v_cvt_pk_bf16_f32 v145, v18, v19
	v_cvt_pk_bf16_f32 v146, v20, v21
	v_cvt_pk_bf16_f32 v147, v22, v23
	v_cvt_pk_bf16_f32 v148, v24, v25
	v_cvt_pk_bf16_f32 v149, v26, v27
	v_cvt_pk_bf16_f32 v150, v28, v29
	v_cvt_pk_bf16_f32 v151, v30, v31
	v_cvt_pk_bf16_f32 v192, v0, v1
	v_cvt_pk_bf16_f32 v193, v2, v3
	v_cvt_pk_bf16_f32 v194, v4, v5
	v_cvt_pk_bf16_f32 v195, v6, v7
	v_cvt_pk_bf16_f32 v196, v8, v9
	v_cvt_pk_bf16_f32 v197, v10, v11
	v_cvt_pk_bf16_f32 v198, v12, v13
	v_cvt_pk_bf16_f32 v199, v14, v15
	v_lshl_add_u64 v[200:201], v[200:201], 0, v[152:153]
	s_nop 1
	v_permlane32_swap_b32_e32 v144, v146
	v_permlane32_swap_b32_e32 v145, v147
	v_permlane32_swap_b32_e32 v148, v150
	v_permlane32_swap_b32_e32 v149, v151
	v_permlane32_swap_b32_e32 v192, v194
	v_permlane32_swap_b32_e32 v193, v195
	v_permlane32_swap_b32_e32 v196, v198
	v_permlane32_swap_b32_e32 v197, v199
	global_store_dwordx4 v[200:201], v[144:147], off
	global_store_dwordx4 v[200:201], v[148:151], off offset:32
	global_store_dwordx4 v[200:201], v[192:195], off offset:64
	global_store_dwordx4 v[200:201], v[196:199], off offset:96


	s_mov_b64 s[12:13], 0
